# weight-convert (map) units: exact counted vmcnt instead of the conservative waits hipcc emits around predicated loads, so tile t+1/t+2 loads stay in flight (P0 and M2 L0 copies)
# speedup vs baseline: 1.0057x; 1.0016x over previous
; #define LAS __attribute__((address_space(3)))
;     template <class T> __device__ __forceinline__ T* w(size_t off) const { return (T*)(pp->ws + off); }
; __device__ __forceinline__ unsigned pk2(float lo, float hi) { return pg8::cvt_pk_bf16(lo, hi); }
; #define CT_LOAD(R, kbase) do { _Pragma("unroll") for (int _it = 0; _it < 4; ++_it) { R[_it][0] = (f32x4){0.f, 0.f, 0.f, 0.f}; R[_it][1] = (f32x4){0.f, 0.f, 0.f, 0.f}; \
;         if (sc >= 0) { const float* _p = src + (size_t)((kbase) + kk + 64 * _it) * src_ld + sc; R[_it][0] = *(const f32x4*)_p; R[_it][1] = *(const f32x4*)(_p + 4); } } } while (0)
; template <bool MAP, int NT>
; __device__ __forceinline__ void convert_tiles(const Ctx& c, const float* src, int src_ld, bf16* dst, int n0, int k0) {
;     ...
;     CT_LOAD(ra, k0);
; #pragma unroll
;     for (int t = 0; t < NT; ++t) {
;         if (t + 1 < NT) CT_LOAD(rb, k0 + (t + 1) * 256);
;         if (t) __syncthreads();
; #pragma unroll
;         for (int it = 0; it < 4; ++it) {
;             LAS unsigned* tp = tile + (kk + 64 * it) * 37 + (c8 >> 1);
;             tp[0] = pk2(ra[it][0][0], ra[it][0][1]); tp[1] = pk2(ra[it][0][2], ra[it][0][3]); tp[2] = pk2(ra[it][1][0], ra[it][1][1]); tp[3] = pk2(ra[it][1][2], ra[it][1][3]);
;         }
;         __syncthreads();
;         const LAS bf16* th = (const LAS bf16*)tile;
; #pragma unroll
;         for (int it = 0; it < 4; ++it) {
;             const int k8 = ks * 8 + 64 * it;
;             unsigned v[8];
; #pragma unroll
;             for (int i = 0; i < 8; ++i) v[i] = th[(k8 + i) * 74 + nn];
;             u32x4 w; w.x = v[0] | (v[1] << 16); w.y = v[2] | (v[3] << 16); w.z = v[4] | (v[5] << 16); w.w = v[6] | (v[7] << 16);
;             *(u32x4*)(dst + (size_t)(n0 + nn) * 4096 + k0 + t * 256 + k8) = w;
.LBB0_53:
	s_or_b64 exec, exec, s[4:5]
	v_add_u32_e32 v67, v65, v66
	v_lshl_add_u32 v75, v74, 1, v65
	v_add_u32_e32 v65, v67, v73
	s_waitcnt vmcnt(8)
	v_cvt_pk_bf16_f32 v20, v20, v21
	ds_write_b32 v65, v20
	v_cvt_pk_bf16_f32 v20, v22, v23
	ds_write_b32 v65, v20 offset:4
	v_cvt_pk_bf16_f32 v12, v12, v13
	ds_write_b32 v65, v12 offset:8
	v_cvt_pk_bf16_f32 v12, v14, v15
	ds_write_b32 v65, v12 offset:12
	v_cvt_pk_bf16_f32 v12, v28, v29
	ds_write_b32 v65, v12 offset:9472
	v_cvt_pk_bf16_f32 v12, v30, v31
	ds_write_b32 v65, v12 offset:9476
	v_cvt_pk_bf16_f32 v4, v4, v5
	ds_write_b32 v65, v4 offset:9480
	v_cvt_pk_bf16_f32 v4, v6, v7
	ds_write_b32 v65, v4 offset:9484
	v_cvt_pk_bf16_f32 v4, v48, v49
	ds_write_b32 v65, v4 offset:18944
	v_cvt_pk_bf16_f32 v4, v50, v51
	ds_write_b32 v65, v4 offset:18948
	v_cvt_pk_bf16_f32 v4, v40, v41
	ds_write_b32 v65, v4 offset:18952
	v_cvt_pk_bf16_f32 v4, v42, v43
	ds_write_b32 v65, v4 offset:18956
	v_cvt_pk_bf16_f32 v4, v56, v57
	ds_write_b32 v65, v4 offset:28416
	v_cvt_pk_bf16_f32 v4, v58, v59
	ds_write_b32 v65, v4 offset:28420
	v_cvt_pk_bf16_f32 v4, v32, v33
	v_add_u32_e32 v76, s8, v74
	ds_write_b32 v65, v4 offset:28424
	v_cvt_pk_bf16_f32 v4, v34, v35
	v_mad_u32_u24 v14, v72, s52, v75
	v_ashrrev_i32_e32 v77, 31, v76
	ds_write_b32 v65, v4 offset:28428
	s_waitcnt lgkmcnt(0)
	s_barrier
	ds_read_u16 v4, v14
	ds_read_u16 v5, v14 offset:148
	ds_read_u16 v6, v14 offset:296
	ds_read_u16 v7, v14 offset:444
	ds_read_u16 v15, v14 offset:592
	ds_read_u16 v20, v14 offset:740
	ds_read_u16 v21, v14 offset:888
	ds_read_u16 v22, v14 offset:1036
	v_lshlrev_b64 v[76:77], 13, v[76:77]
	v_lshl_add_u64 v[76:77], s[0:1], 0, v[76:77]
	s_lshl_b32 s8, s43, 1
	v_lshl_add_u64 v[12:13], v[76:77], 0, s[8:9]
	v_mov_b32_e32 v67, v165
	v_lshl_add_u64 v[12:13], v[12:13], 0, v[66:67]
	s_waitcnt lgkmcnt(6)
	v_lshl_or_b32 v4, v5, 16, v4
	s_waitcnt lgkmcnt(4)
	v_lshl_or_b32 v5, v7, 16, v6
	s_waitcnt lgkmcnt(2)
	v_lshl_or_b32 v6, v20, 16, v15
	s_waitcnt lgkmcnt(0)
	v_lshl_or_b32 v7, v22, 16, v21
	v_lshl_add_u64 v[66:67], v[12:13], 0, s[12:13]
	v_add_co_u32_e64 v12, s[0:1], s50, v12
	ds_read_u16 v15, v14 offset:9472
	ds_read_u16 v20, v14 offset:9620
	ds_read_u16 v21, v14 offset:9768
	ds_read_u16 v22, v14 offset:9916
	ds_read_u16 v23, v14 offset:10064
	ds_read_u16 v28, v14 offset:10212
	ds_read_u16 v29, v14 offset:10360
	ds_read_u16 v30, v14 offset:10508
	v_addc_co_u32_e64 v13, s[0:1], 0, v13, s[0:1]
	global_store_dwordx4 v[12:13], v[4:7], off
	s_waitcnt lgkmcnt(6)
	s_nop 0
	v_lshl_or_b32 v4, v20, 16, v15
	s_waitcnt lgkmcnt(4)
	v_lshl_or_b32 v5, v22, 16, v21
	s_waitcnt lgkmcnt(2)
	v_lshl_or_b32 v6, v28, 16, v23
	ds_read_u16 v12, v14 offset:18944
	ds_read_u16 v13, v14 offset:19092
	ds_read_u16 v15, v14 offset:19240
	ds_read_u16 v20, v14 offset:19388
	ds_read_u16 v21, v14 offset:19536
	ds_read_u16 v22, v14 offset:19684
	ds_read_u16 v23, v14 offset:19832
	ds_read_u16 v28, v14 offset:19980
	s_waitcnt lgkmcnt(8)
	v_lshl_or_b32 v7, v30, 16, v29
	global_store_dwordx4 v[66:67], v[4:7], off offset:128
	s_waitcnt lgkmcnt(6)
	s_nop 0
	v_lshl_or_b32 v4, v13, 16, v12
	s_waitcnt lgkmcnt(4)
	v_lshl_or_b32 v5, v20, 16, v15
	s_waitcnt lgkmcnt(2)
	v_lshl_or_b32 v6, v22, 16, v21
	s_waitcnt lgkmcnt(0)
	v_lshl_or_b32 v7, v28, 16, v23
	ds_read_u16 v12, v14 offset:28416
	ds_read_u16 v13, v14 offset:28564
	ds_read_u16 v15, v14 offset:28712
	ds_read_u16 v20, v14 offset:28860
	ds_read_u16 v21, v14 offset:29008
	ds_read_u16 v22, v14 offset:29156
	ds_read_u16 v23, v14 offset:29304
	ds_read_u16 v14, v14 offset:29452
	global_store_dwordx4 v[66:67], v[4:7], off offset:256
	s_waitcnt lgkmcnt(6)
	s_nop 0
	v_lshl_or_b32 v4, v13, 16, v12
	s_waitcnt lgkmcnt(4)
	v_lshl_or_b32 v5, v20, 16, v15
	s_waitcnt lgkmcnt(2)
	v_lshl_or_b32 v6, v22, 16, v21
	s_waitcnt lgkmcnt(0)
	v_lshl_or_b32 v7, v14, 16, v23
	global_store_dwordx4 v[66:67], v[4:7], off offset:384
	v_mov_b32_e32 v12, 0
	v_mov_b32_e32 v13, 0
	v_mov_b32_e32 v4, 0
	v_mov_b32_e32 v14, 0
	v_mov_b32_e32 v15, 0
	v_mov_b32_e32 v20, 0
	v_mov_b32_e32 v21, 0
	v_mov_b32_e32 v22, 0
	v_mov_b32_e32 v23, 0
	s_and_saveexec_b64 s[0:1], vcc
	s_cbranch_execz .LBB0_55
	v_add_u32_e32 v5, 0x200, v64
	v_mad_i64_i32 v[6:7], s[4:5], v5, s65, v[68:69]
	global_load_dwordx4 v[12:15], v[6:7], off offset:16
	global_load_dwordx4 v[20:23], v[6:7], off

; #define LAS __attribute__((address_space(3)))
;     template <class T> __device__ __forceinline__ T* w(size_t off) const { return (T*)(pp->ws + off); }
; __device__ __forceinline__ unsigned pk2(float lo, float hi) { return pg8::cvt_pk_bf16(lo, hi); }
; #define CT_LOAD(R, kbase) do { _Pragma("unroll") for (int _it = 0; _it < 4; ++_it) { R[_it][0] = (f32x4){0.f, 0.f, 0.f, 0.f}; R[_it][1] = (f32x4){0.f, 0.f, 0.f, 0.f}; \
;         if (sc >= 0) { const float* _p = src + (size_t)((kbase) + kk + 64 * _it) * src_ld + sc; R[_it][0] = *(const f32x4*)_p; R[_it][1] = *(const f32x4*)(_p + 4); } } } while (0)
; template <bool MAP, int NT>
; __device__ __forceinline__ void convert_tiles(const Ctx& c, const float* src, int src_ld, bf16* dst, int n0, int k0) {
;     ...
;     CT_LOAD(ra, k0);
; #pragma unroll
;     for (int t = 0; t < NT; ++t) {
;         if (t + 1 < NT) CT_LOAD(rb, k0 + (t + 1) * 256);
;         if (t) __syncthreads();
; #pragma unroll
;         for (int it = 0; it < 4; ++it) {
;             LAS unsigned* tp = tile + (kk + 64 * it) * 37 + (c8 >> 1);
;             tp[0] = pk2(ra[it][0][0], ra[it][0][1]); tp[1] = pk2(ra[it][0][2], ra[it][0][3]); tp[2] = pk2(ra[it][1][0], ra[it][1][1]); tp[3] = pk2(ra[it][1][2], ra[it][1][3]);
;         }
;         __syncthreads();
;         const LAS bf16* th = (const LAS bf16*)tile;
; #pragma unroll
;         for (int it = 0; it < 4; ++it) {
;             const int k8 = ks * 8 + 64 * it;
;             unsigned v[8];
; #pragma unroll
;             for (int i = 0; i < 8; ++i) v[i] = th[(k8 + i) * 74 + nn];
;             u32x4 w; w.x = v[0] | (v[1] << 16); w.y = v[2] | (v[3] << 16); w.z = v[4] | (v[5] << 16); w.w = v[6] | (v[7] << 16);
;             *(u32x4*)(dst + (size_t)(n0 + nn) * 4096 + k0 + t * 256 + k8) = w;
.LBB0_61:
	s_or_b64 exec, exec, s[0:1]
	s_barrier
	s_waitcnt vmcnt(12)
	v_cvt_pk_bf16_f32 v16, v16, v17
	ds_write_b32 v65, v16
	v_cvt_pk_bf16_f32 v16, v18, v19
	ds_write_b32 v65, v16 offset:4
	v_cvt_pk_bf16_f32 v8, v8, v9
	ds_write_b32 v65, v8 offset:8
	v_cvt_pk_bf16_f32 v8, v10, v11
	ds_write_b32 v65, v8 offset:12
	v_cvt_pk_bf16_f32 v8, v24, v25
	ds_write_b32 v65, v8 offset:9472
	v_cvt_pk_bf16_f32 v8, v26, v27
	ds_write_b32 v65, v8 offset:9476
	v_cvt_pk_bf16_f32 v0, v0, v1
	ds_write_b32 v65, v0 offset:9480
	v_cvt_pk_bf16_f32 v0, v2, v3
	ds_write_b32 v65, v0 offset:9484
	v_cvt_pk_bf16_f32 v0, v52, v53
	ds_write_b32 v65, v0 offset:18944
	v_cvt_pk_bf16_f32 v0, v54, v55
	ds_write_b32 v65, v0 offset:18948
	v_cvt_pk_bf16_f32 v0, v44, v45
	ds_write_b32 v65, v0 offset:18952
	v_cvt_pk_bf16_f32 v0, v46, v47
	ds_write_b32 v65, v0 offset:18956
	v_cvt_pk_bf16_f32 v0, v60, v61
	ds_write_b32 v65, v0 offset:28416
	v_cvt_pk_bf16_f32 v0, v62, v63
	ds_write_b32 v65, v0 offset:28420
	v_cvt_pk_bf16_f32 v0, v36, v37
	ds_write_b32 v65, v0 offset:28424
	v_cvt_pk_bf16_f32 v0, v38, v39
	v_add_u32_e32 v71, v75, v71
	ds_write_b32 v65, v0 offset:28428
	s_waitcnt lgkmcnt(0)
	s_barrier
	ds_read_u16 v0, v71
	ds_read_u16 v1, v71 offset:148
	ds_read_u16 v2, v71 offset:296
	ds_read_u16 v3, v71 offset:444
	ds_read_u16 v8, v71 offset:592
	ds_read_u16 v9, v71 offset:740
	ds_read_u16 v10, v71 offset:888
	ds_read_u16 v11, v71 offset:1036
	s_waitcnt lgkmcnt(6)
	v_lshl_or_b32 v0, v1, 16, v0
	s_waitcnt lgkmcnt(4)
	v_lshl_or_b32 v1, v3, 16, v2
	s_waitcnt lgkmcnt(2)
	v_lshl_or_b32 v2, v9, 16, v8
	s_waitcnt lgkmcnt(0)
	v_lshl_or_b32 v3, v11, 16, v10
	ds_read_u16 v8, v71 offset:9472
	ds_read_u16 v9, v71 offset:9620
	ds_read_u16 v10, v71 offset:9768
	ds_read_u16 v11, v71 offset:9916
	ds_read_u16 v16, v71 offset:10064
	ds_read_u16 v17, v71 offset:10212
	ds_read_u16 v18, v71 offset:10360
	ds_read_u16 v19, v71 offset:10508
	global_store_dwordx4 v[66:67], v[0:3], off offset:512
	s_waitcnt lgkmcnt(6)
	s_nop 0
	v_lshl_or_b32 v0, v9, 16, v8
	s_waitcnt lgkmcnt(4)
	v_lshl_or_b32 v1, v11, 16, v10
	s_waitcnt lgkmcnt(2)
	v_lshl_or_b32 v2, v17, 16, v16
	s_waitcnt lgkmcnt(0)
	v_lshl_or_b32 v3, v19, 16, v18
	ds_read_u16 v8, v71 offset:18944
	ds_read_u16 v9, v71 offset:19092
	ds_read_u16 v10, v71 offset:19240
	ds_read_u16 v11, v71 offset:19388
	ds_read_u16 v16, v71 offset:19536
	ds_read_u16 v17, v71 offset:19684
	ds_read_u16 v18, v71 offset:19832
	ds_read_u16 v19, v71 offset:19980
	global_store_dwordx4 v[66:67], v[0:3], off offset:640
	s_waitcnt lgkmcnt(6)
	s_nop 0
	v_lshl_or_b32 v0, v9, 16, v8
	s_waitcnt lgkmcnt(4)
	v_lshl_or_b32 v1, v11, 16, v10
	s_waitcnt lgkmcnt(2)
	v_lshl_or_b32 v2, v17, 16, v16
	s_waitcnt lgkmcnt(0)
	v_lshl_or_b32 v3, v19, 16, v18
	ds_read_u16 v8, v71 offset:28416
	ds_read_u16 v9, v71 offset:28564
	ds_read_u16 v10, v71 offset:28712
	ds_read_u16 v11, v71 offset:28860
	ds_read_u16 v16, v71 offset:29008
	ds_read_u16 v17, v71 offset:29156
	ds_read_u16 v18, v71 offset:29304
	ds_read_u16 v19, v71 offset:29452
	global_store_dwordx4 v[66:67], v[0:3], off offset:768
	s_waitcnt lgkmcnt(6)
	s_nop 0
	v_lshl_or_b32 v0, v9, 16, v8
	s_waitcnt lgkmcnt(4)
	v_lshl_or_b32 v1, v11, 16, v10
	s_waitcnt lgkmcnt(2)
	v_lshl_or_b32 v2, v17, 16, v16
	s_waitcnt lgkmcnt(0)
	v_lshl_or_b32 v3, v19, 16, v18
	global_store_dwordx4 v[66:67], v[0:3], off offset:896
	v_mov_b32_e32 v8, 0
	v_mov_b32_e32 v9, 0
	v_mov_b32_e32 v0, 0
	v_mov_b32_e32 v10, 0
	v_mov_b32_e32 v11, 0
	v_mov_b32_e32 v16, 0
	v_mov_b32_e32 v17, 0
	v_mov_b32_e32 v18, 0
	v_mov_b32_e32 v19, 0
	s_and_saveexec_b64 s[0:1], vcc
	s_cbranch_execz .LBB0_63
	v_add_u32_e32 v1, 0x300, v64
	v_mad_i64_i32 v[2:3], s[4:5], v1, s65, v[68:69]
	global_load_dwordx4 v[8:11], v[2:3], off offset:16
	global_load_dwordx4 v[16:19], v[2:3], off

; #define LAS __attribute__((address_space(3)))
;     template <class T> __device__ __forceinline__ T* w(size_t off) const { return (T*)(pp->ws + off); }
; __device__ __forceinline__ unsigned pk2(float lo, float hi) { return pg8::cvt_pk_bf16(lo, hi); }
; #define CT_LOAD(R, kbase) do { _Pragma("unroll") for (int _it = 0; _it < 4; ++_it) { R[_it][0] = (f32x4){0.f, 0.f, 0.f, 0.f}; R[_it][1] = (f32x4){0.f, 0.f, 0.f, 0.f}; \
;         if (sc >= 0) { const float* _p = src + (size_t)((kbase) + kk + 64 * _it) * src_ld + sc; R[_it][0] = *(const f32x4*)_p; R[_it][1] = *(const f32x4*)(_p + 4); } } } while (0)
; template <bool MAP, int NT>
; __device__ __forceinline__ void convert_tiles(const Ctx& c, const float* src, int src_ld, bf16* dst, int n0, int k0) {
;     ...
;         if (t + 1 < NT) CT_LOAD(rb, k0 + (t + 1) * 256);
;         if (t) __syncthreads();
; #pragma unroll
;         for (int it = 0; it < 4; ++it) {
;             LAS unsigned* tp = tile + (kk + 64 * it) * 37 + (c8 >> 1);
;             tp[0] = pk2(ra[it][0][0], ra[it][0][1]); tp[1] = pk2(ra[it][0][2], ra[it][0][3]); tp[2] = pk2(ra[it][1][0], ra[it][1][1]); tp[3] = pk2(ra[it][1][2], ra[it][1][3]);
;         }
;         __syncthreads();
;         const LAS bf16* th = (const LAS bf16*)tile;
; #pragma unroll
;         for (int it = 0; it < 4; ++it) {
;             const int k8 = ks * 8 + 64 * it;
;             unsigned v[8];
; #pragma unroll
;             for (int i = 0; i < 8; ++i) v[i] = th[(k8 + i) * 74 + nn];
;             u32x4 w; w.x = v[0] | (v[1] << 16); w.y = v[2] | (v[3] << 16); w.z = v[4] | (v[5] << 16); w.w = v[6] | (v[7] << 16);
;             *(u32x4*)(dst + (size_t)(n0 + nn) * 4096 + k0 + t * 256 + k8) = w;
.LBB0_69:
	s_or_b64 exec, exec, s[0:1]
	s_barrier
	s_waitcnt vmcnt(12)
	v_cvt_pk_bf16_f32 v20, v20, v21
	ds_write_b32 v65, v20
	v_cvt_pk_bf16_f32 v20, v22, v23
	ds_write_b32 v65, v20 offset:4
	v_cvt_pk_bf16_f32 v12, v12, v13
	ds_write_b32 v65, v12 offset:8
	v_cvt_pk_bf16_f32 v12, v14, v15
	ds_write_b32 v65, v12 offset:12
	v_cvt_pk_bf16_f32 v12, v32, v33
	ds_write_b32 v65, v12 offset:9472
	v_cvt_pk_bf16_f32 v12, v34, v35
	ds_write_b32 v65, v12 offset:9476
	v_cvt_pk_bf16_f32 v4, v4, v5
	ds_write_b32 v65, v4 offset:9480
	v_cvt_pk_bf16_f32 v4, v6, v7
	ds_write_b32 v65, v4 offset:9484
	v_cvt_pk_bf16_f32 v4, v48, v49
	ds_write_b32 v65, v4 offset:18944
	v_cvt_pk_bf16_f32 v4, v50, v51
	ds_write_b32 v65, v4 offset:18948
	v_cvt_pk_bf16_f32 v4, v40, v41
	ds_write_b32 v65, v4 offset:18952
	v_cvt_pk_bf16_f32 v4, v42, v43
	ds_write_b32 v65, v4 offset:18956
	v_cvt_pk_bf16_f32 v4, v56, v57
	ds_write_b32 v65, v4 offset:28416
	v_cvt_pk_bf16_f32 v4, v58, v59
	ds_write_b32 v65, v4 offset:28420
	v_cvt_pk_bf16_f32 v4, v28, v29
	ds_write_b32 v65, v4 offset:28424
	v_cvt_pk_bf16_f32 v4, v30, v31
	ds_write_b32 v65, v4 offset:28428
	s_waitcnt lgkmcnt(0)
	s_barrier
	ds_read_u16 v4, v71
	ds_read_u16 v5, v71 offset:148
	ds_read_u16 v6, v71 offset:296
	ds_read_u16 v7, v71 offset:444
	ds_read_u16 v12, v71 offset:592
	ds_read_u16 v13, v71 offset:740
	ds_read_u16 v14, v71 offset:888
	ds_read_u16 v15, v71 offset:1036
	s_waitcnt lgkmcnt(6)
	v_lshl_or_b32 v4, v5, 16, v4
	s_waitcnt lgkmcnt(4)
	v_lshl_or_b32 v5, v7, 16, v6
	s_waitcnt lgkmcnt(2)
	v_lshl_or_b32 v6, v13, 16, v12
	s_waitcnt lgkmcnt(0)
	v_lshl_or_b32 v7, v15, 16, v14
	ds_read_u16 v12, v71 offset:9472
	ds_read_u16 v13, v71 offset:9620
	ds_read_u16 v14, v71 offset:9768
	ds_read_u16 v15, v71 offset:9916
	ds_read_u16 v20, v71 offset:10064
	ds_read_u16 v21, v71 offset:10212
	ds_read_u16 v22, v71 offset:10360
	ds_read_u16 v23, v71 offset:10508
	global_store_dwordx4 v[66:67], v[4:7], off offset:1024
	s_waitcnt lgkmcnt(6)
	s_nop 0
	v_lshl_or_b32 v4, v13, 16, v12
	s_waitcnt lgkmcnt(4)
	v_lshl_or_b32 v5, v15, 16, v14
	s_waitcnt lgkmcnt(2)
	v_lshl_or_b32 v6, v21, 16, v20
	s_waitcnt lgkmcnt(0)
	v_lshl_or_b32 v7, v23, 16, v22
	ds_read_u16 v12, v71 offset:18944
	ds_read_u16 v13, v71 offset:19092
	ds_read_u16 v14, v71 offset:19240
	ds_read_u16 v15, v71 offset:19388
	ds_read_u16 v20, v71 offset:19536
	ds_read_u16 v21, v71 offset:19684
	ds_read_u16 v22, v71 offset:19832
	ds_read_u16 v23, v71 offset:19980
	global_store_dwordx4 v[66:67], v[4:7], off offset:1152
	s_waitcnt lgkmcnt(6)
	s_nop 0
	v_lshl_or_b32 v4, v13, 16, v12
	s_waitcnt lgkmcnt(4)
	v_lshl_or_b32 v5, v15, 16, v14
	s_waitcnt lgkmcnt(2)
	v_lshl_or_b32 v6, v21, 16, v20
	s_waitcnt lgkmcnt(0)
	v_lshl_or_b32 v7, v23, 16, v22
	ds_read_u16 v12, v71 offset:28416
	ds_read_u16 v13, v71 offset:28564
	ds_read_u16 v14, v71 offset:28712
	ds_read_u16 v15, v71 offset:28860
	ds_read_u16 v20, v71 offset:29008
	ds_read_u16 v21, v71 offset:29156
	ds_read_u16 v22, v71 offset:29304
	ds_read_u16 v23, v71 offset:29452
	global_store_dwordx4 v[66:67], v[4:7], off offset:1280
	s_waitcnt lgkmcnt(6)
	s_nop 0
	v_lshl_or_b32 v4, v13, 16, v12
	s_waitcnt lgkmcnt(4)
	v_lshl_or_b32 v5, v15, 16, v14
	s_waitcnt lgkmcnt(2)
	v_lshl_or_b32 v6, v21, 16, v20
	s_waitcnt lgkmcnt(0)
	v_lshl_or_b32 v7, v23, 16, v22
	global_store_dwordx4 v[66:67], v[4:7], off offset:1408
	s_barrier
	s_waitcnt vmcnt(4)
	v_cvt_pk_bf16_f32 v4, v16, v17
	ds_write_b32 v65, v4
	v_cvt_pk_bf16_f32 v4, v18, v19
	ds_write_b32 v65, v4 offset:4
	v_cvt_pk_bf16_f32 v4, v8, v9
	ds_write_b32 v65, v4 offset:8
	v_cvt_pk_bf16_f32 v4, v10, v11
	ds_write_b32 v65, v4 offset:12
	v_cvt_pk_bf16_f32 v4, v36, v37
	ds_write_b32 v65, v4 offset:9472
	v_cvt_pk_bf16_f32 v4, v38, v39
	ds_write_b32 v65, v4 offset:9476
	v_cvt_pk_bf16_f32 v0, v0, v1
	ds_write_b32 v65, v0 offset:9480
	v_cvt_pk_bf16_f32 v0, v2, v3
	ds_write_b32 v65, v0 offset:9484
	v_cvt_pk_bf16_f32 v0, v52, v53
	ds_write_b32 v65, v0 offset:18944
	v_cvt_pk_bf16_f32 v0, v54, v55
	ds_write_b32 v65, v0 offset:18948
	v_cvt_pk_bf16_f32 v0, v44, v45
	ds_write_b32 v65, v0 offset:18952
	v_cvt_pk_bf16_f32 v0, v46, v47
	ds_write_b32 v65, v0 offset:18956
	v_cvt_pk_bf16_f32 v0, v60, v61
	ds_write_b32 v65, v0 offset:28416
	v_cvt_pk_bf16_f32 v0, v62, v63
	ds_write_b32 v65, v0 offset:28420
	v_cvt_pk_bf16_f32 v0, v24, v25
	ds_write_b32 v65, v0 offset:28424
	v_cvt_pk_bf16_f32 v0, v26, v27
	ds_write_b32 v65, v0 offset:28428
	s_waitcnt lgkmcnt(0)
	s_barrier
	ds_read_u16 v0, v71
	ds_read_u16 v1, v71 offset:148
	ds_read_u16 v2, v71 offset:296
	ds_read_u16 v3, v71 offset:444
	ds_read_u16 v4, v71 offset:592
	ds_read_u16 v5, v71 offset:740
	ds_read_u16 v6, v71 offset:888
	ds_read_u16 v7, v71 offset:1036
	s_waitcnt lgkmcnt(6)
	v_lshl_or_b32 v0, v1, 16, v0
	s_waitcnt lgkmcnt(4)
	v_lshl_or_b32 v1, v3, 16, v2
	s_waitcnt lgkmcnt(2)
	v_lshl_or_b32 v2, v5, 16, v4
	s_waitcnt lgkmcnt(0)
	v_lshl_or_b32 v3, v7, 16, v6
	ds_read_u16 v4, v71 offset:9472
	ds_read_u16 v5, v71 offset:9620
	ds_read_u16 v6, v71 offset:9768
	ds_read_u16 v7, v71 offset:9916
	ds_read_u16 v8, v71 offset:10064
	ds_read_u16 v9, v71 offset:10212
	ds_read_u16 v10, v71 offset:10360
	ds_read_u16 v11, v71 offset:10508
	global_store_dwordx4 v[66:67], v[0:3], off offset:1536
	s_waitcnt lgkmcnt(6)
	s_nop 0
	v_lshl_or_b32 v0, v5, 16, v4
	s_waitcnt lgkmcnt(4)
	v_lshl_or_b32 v1, v7, 16, v6
	s_waitcnt lgkmcnt(2)
	v_lshl_or_b32 v2, v9, 16, v8
	s_waitcnt lgkmcnt(0)
	v_lshl_or_b32 v3, v11, 16, v10
	ds_read_u16 v4, v71 offset:18944
	ds_read_u16 v5, v71 offset:19092
	ds_read_u16 v6, v71 offset:19240
	ds_read_u16 v7, v71 offset:19388
	ds_read_u16 v8, v71 offset:19536
	ds_read_u16 v9, v71 offset:19684
	ds_read_u16 v10, v71 offset:19832
	ds_read_u16 v11, v71 offset:19980
	global_store_dwordx4 v[66:67], v[0:3], off offset:1664
	s_waitcnt lgkmcnt(6)
	s_nop 0
	v_lshl_or_b32 v0, v5, 16, v4
	s_waitcnt lgkmcnt(4)
	v_lshl_or_b32 v1, v7, 16, v6
	s_waitcnt lgkmcnt(2)
	v_lshl_or_b32 v2, v9, 16, v8
	s_waitcnt lgkmcnt(0)
	v_lshl_or_b32 v3, v11, 16, v10
	ds_read_u16 v4, v71 offset:28416
	ds_read_u16 v5, v71 offset:28564
	ds_read_u16 v6, v71 offset:28712
	ds_read_u16 v7, v71 offset:28860
	ds_read_u16 v8, v71 offset:29008
	ds_read_u16 v9, v71 offset:29156
	ds_read_u16 v10, v71 offset:29304
	ds_read_u16 v11, v71 offset:29452
	global_store_dwordx4 v[66:67], v[0:3], off offset:1792
	s_waitcnt lgkmcnt(6)
	s_nop 0
	v_lshl_or_b32 v0, v5, 16, v4
	s_waitcnt lgkmcnt(4)
	v_lshl_or_b32 v1, v7, 16, v6
	s_waitcnt lgkmcnt(2)
	v_lshl_or_b32 v2, v9, 16, v8
	s_waitcnt lgkmcnt(0)
	v_lshl_or_b32 v3, v11, 16, v10
	global_store_dwordx4 v[66:67], v[0:3], off offset:1920

; #define LAS __attribute__((address_space(3)))
;     template <class T> __device__ __forceinline__ T* w(size_t off) const { return (T*)(pp->ws + off); }
; __device__ __forceinline__ unsigned pk2(float lo, float hi) { return pg8::cvt_pk_bf16(lo, hi); }
; #define CT_LOAD(R, kbase) do { _Pragma("unroll") for (int _it = 0; _it < 4; ++_it) { R[_it][0] = (f32x4){0.f, 0.f, 0.f, 0.f}; R[_it][1] = (f32x4){0.f, 0.f, 0.f, 0.f}; \
;         if (sc >= 0) { const float* _p = src + (size_t)((kbase) + kk + 64 * _it) * src_ld + sc; R[_it][0] = *(const f32x4*)_p; R[_it][1] = *(const f32x4*)(_p + 4); } } } while (0)
; template <bool MAP, int NT>
; __device__ __forceinline__ void convert_tiles(const Ctx& c, const float* src, int src_ld, bf16* dst, int n0, int k0) {
;     ...
;     CT_LOAD(ra, k0);
; #pragma unroll
;     for (int t = 0; t < NT; ++t) {
;         if (t + 1 < NT) CT_LOAD(rb, k0 + (t + 1) * 256);
;         if (t) __syncthreads();
; #pragma unroll
;         for (int it = 0; it < 4; ++it) {
;             LAS unsigned* tp = tile + (kk + 64 * it) * 37 + (c8 >> 1);
;             tp[0] = pk2(ra[it][0][0], ra[it][0][1]); tp[1] = pk2(ra[it][0][2], ra[it][0][3]); tp[2] = pk2(ra[it][1][0], ra[it][1][1]); tp[3] = pk2(ra[it][1][2], ra[it][1][3]);
;         }
;         __syncthreads();
;         const LAS bf16* th = (const LAS bf16*)tile;
; #pragma unroll
;         for (int it = 0; it < 4; ++it) {
;             const int k8 = ks * 8 + 64 * it;
;             unsigned v[8];
; #pragma unroll
;             for (int i = 0; i < 8; ++i) v[i] = th[(k8 + i) * 74 + nn];
;             u32x4 w; w.x = v[0] | (v[1] << 16); w.y = v[2] | (v[3] << 16); w.z = v[4] | (v[5] << 16); w.w = v[6] | (v[7] << 16);
;             *(u32x4*)(dst + (size_t)(n0 + nn) * 4096 + k0 + t * 256 + k8) = w;
.LBB0_1399:
	s_or_b64 exec, exec, s[2:3]
	v_add_u32_e32 v67, v65, v66
	v_lshl_add_u32 v70, v75, 1, v65
	v_add_u32_e32 v65, v67, v74
	s_waitcnt vmcnt(8)
	v_cvt_pk_bf16_f32 v20, v20, v21
	ds_write_b32 v65, v20
	v_cvt_pk_bf16_f32 v20, v22, v23
	ds_write_b32 v65, v20 offset:4
	v_cvt_pk_bf16_f32 v12, v12, v13
	ds_write_b32 v65, v12 offset:8
	v_cvt_pk_bf16_f32 v12, v14, v15
	ds_write_b32 v65, v12 offset:12
	v_cvt_pk_bf16_f32 v12, v28, v29
	ds_write_b32 v65, v12 offset:9472
	v_cvt_pk_bf16_f32 v12, v30, v31
	ds_write_b32 v65, v12 offset:9476
	v_cvt_pk_bf16_f32 v4, v4, v5
	ds_write_b32 v65, v4 offset:9480
	v_cvt_pk_bf16_f32 v4, v6, v7
	ds_write_b32 v65, v4 offset:9484
	v_cvt_pk_bf16_f32 v4, v52, v53
	ds_write_b32 v65, v4 offset:18944
	v_cvt_pk_bf16_f32 v4, v54, v55
	ds_write_b32 v65, v4 offset:18948
	v_cvt_pk_bf16_f32 v4, v40, v41
	ds_write_b32 v65, v4 offset:18952
	v_cvt_pk_bf16_f32 v4, v42, v43
	ds_write_b32 v65, v4 offset:18956
	v_cvt_pk_bf16_f32 v4, v56, v57
	ds_write_b32 v65, v4 offset:28416
	v_cvt_pk_bf16_f32 v4, v58, v59
	ds_write_b32 v65, v4 offset:28420
	v_cvt_pk_bf16_f32 v4, v32, v33
	v_add_u32_e32 v76, s18, v75
	ds_write_b32 v65, v4 offset:28424
	v_cvt_pk_bf16_f32 v4, v34, v35
	v_mad_u32_u24 v14, v73, s75, v70
	v_ashrrev_i32_e32 v77, 31, v76
	ds_write_b32 v65, v4 offset:28428
	s_waitcnt lgkmcnt(0)
	s_barrier
	ds_read_u16 v4, v14
	ds_read_u16 v5, v14 offset:148
	ds_read_u16 v6, v14 offset:296
	ds_read_u16 v7, v14 offset:444
	ds_read_u16 v15, v14 offset:592
	ds_read_u16 v20, v14 offset:740
	ds_read_u16 v21, v14 offset:888
	ds_read_u16 v22, v14 offset:1036
	v_lshlrev_b64 v[76:77], 13, v[76:77]
	v_lshl_add_u64 v[76:77], s[0:1], 0, v[76:77]
	s_lshl_b32 s18, s9, 1
	v_lshl_add_u64 v[12:13], v[76:77], 0, s[18:19]
	v_mov_b32_e32 v67, v161
	v_lshl_add_u64 v[12:13], v[12:13], 0, v[66:67]
	s_mov_b32 s0, 0x7a00000
	s_waitcnt lgkmcnt(6)
	v_lshl_or_b32 v4, v5, 16, v4
	s_waitcnt lgkmcnt(4)
	v_lshl_or_b32 v5, v7, 16, v6
	s_waitcnt lgkmcnt(2)
	v_lshl_or_b32 v6, v20, 16, v15
	s_waitcnt lgkmcnt(0)
	v_lshl_or_b32 v7, v22, 16, v21
	v_lshl_add_u64 v[66:67], v[12:13], 0, s[34:35]
	v_add_co_u32_e64 v12, s[0:1], s0, v12
	ds_read_u16 v15, v14 offset:9472
	ds_read_u16 v20, v14 offset:9620
	ds_read_u16 v21, v14 offset:9768
	ds_read_u16 v22, v14 offset:9916
	ds_read_u16 v23, v14 offset:10064
	ds_read_u16 v28, v14 offset:10212
	ds_read_u16 v29, v14 offset:10360
	ds_read_u16 v30, v14 offset:10508
	v_addc_co_u32_e64 v13, s[0:1], 0, v13, s[0:1]
	global_store_dwordx4 v[12:13], v[4:7], off
	s_waitcnt lgkmcnt(6)
	s_nop 0
	v_lshl_or_b32 v4, v20, 16, v15
	s_waitcnt lgkmcnt(4)
	v_lshl_or_b32 v5, v22, 16, v21
	s_waitcnt lgkmcnt(2)
	v_lshl_or_b32 v6, v28, 16, v23
	ds_read_u16 v12, v14 offset:18944
	ds_read_u16 v13, v14 offset:19092
	ds_read_u16 v15, v14 offset:19240
	ds_read_u16 v20, v14 offset:19388
	ds_read_u16 v21, v14 offset:19536
	ds_read_u16 v22, v14 offset:19684
	ds_read_u16 v23, v14 offset:19832
	ds_read_u16 v28, v14 offset:19980
	s_waitcnt lgkmcnt(8)
	v_lshl_or_b32 v7, v30, 16, v29
	global_store_dwordx4 v[66:67], v[4:7], off offset:128
	s_waitcnt lgkmcnt(6)
	s_nop 0
	v_lshl_or_b32 v4, v13, 16, v12
	s_waitcnt lgkmcnt(4)
	v_lshl_or_b32 v5, v20, 16, v15
	s_waitcnt lgkmcnt(2)
	v_lshl_or_b32 v6, v22, 16, v21
	s_waitcnt lgkmcnt(0)
	v_lshl_or_b32 v7, v28, 16, v23
	ds_read_u16 v12, v14 offset:28416
	ds_read_u16 v13, v14 offset:28564
	ds_read_u16 v15, v14 offset:28712
	ds_read_u16 v20, v14 offset:28860
	ds_read_u16 v21, v14 offset:29008
	ds_read_u16 v22, v14 offset:29156
	ds_read_u16 v23, v14 offset:29304
	ds_read_u16 v14, v14 offset:29452
	global_store_dwordx4 v[66:67], v[4:7], off offset:256
	s_waitcnt lgkmcnt(6)
	s_nop 0
	v_lshl_or_b32 v4, v13, 16, v12
	s_waitcnt lgkmcnt(4)
	v_lshl_or_b32 v5, v20, 16, v15
	s_waitcnt lgkmcnt(2)
	v_lshl_or_b32 v6, v22, 16, v21
	s_waitcnt lgkmcnt(0)
	v_lshl_or_b32 v7, v14, 16, v23
	global_store_dwordx4 v[66:67], v[4:7], off offset:384
	v_mov_b32_e32 v12, 0
	v_mov_b32_e32 v13, 0
	v_mov_b32_e32 v4, 0
	v_mov_b32_e32 v14, 0
	v_mov_b32_e32 v15, 0
	v_mov_b32_e32 v20, 0
	v_mov_b32_e32 v21, 0
	v_mov_b32_e32 v22, 0
	v_mov_b32_e32 v23, 0
	s_and_saveexec_b64 s[0:1], vcc
	s_cbranch_execz .LBB0_1401
	v_add_u32_e32 v5, 0x200, v64
	v_mad_i64_i32 v[6:7], s[2:3], v5, s76, v[68:69]
	global_load_dwordx4 v[12:15], v[6:7], off offset:16
	global_load_dwordx4 v[20:23], v[6:7], off

; #define LAS __attribute__((address_space(3)))
;     template <class T> __device__ __forceinline__ T* w(size_t off) const { return (T*)(pp->ws + off); }
; __device__ __forceinline__ unsigned pk2(float lo, float hi) { return pg8::cvt_pk_bf16(lo, hi); }
; #define CT_LOAD(R, kbase) do { _Pragma("unroll") for (int _it = 0; _it < 4; ++_it) { R[_it][0] = (f32x4){0.f, 0.f, 0.f, 0.f}; R[_it][1] = (f32x4){0.f, 0.f, 0.f, 0.f}; \
;         if (sc >= 0) { const float* _p = src + (size_t)((kbase) + kk + 64 * _it) * src_ld + sc; R[_it][0] = *(const f32x4*)_p; R[_it][1] = *(const f32x4*)(_p + 4); } } } while (0)
; template <bool MAP, int NT>
; __device__ __forceinline__ void convert_tiles(const Ctx& c, const float* src, int src_ld, bf16* dst, int n0, int k0) {
;     ...
;     CT_LOAD(ra, k0);
; #pragma unroll
;     for (int t = 0; t < NT; ++t) {
;         if (t + 1 < NT) CT_LOAD(rb, k0 + (t + 1) * 256);
;         if (t) __syncthreads();
; #pragma unroll
;         for (int it = 0; it < 4; ++it) {
;             LAS unsigned* tp = tile + (kk + 64 * it) * 37 + (c8 >> 1);
;             tp[0] = pk2(ra[it][0][0], ra[it][0][1]); tp[1] = pk2(ra[it][0][2], ra[it][0][3]); tp[2] = pk2(ra[it][1][0], ra[it][1][1]); tp[3] = pk2(ra[it][1][2], ra[it][1][3]);
;         }
;         __syncthreads();
;         const LAS bf16* th = (const LAS bf16*)tile;
; #pragma unroll
;         for (int it = 0; it < 4; ++it) {
;             const int k8 = ks * 8 + 64 * it;
;             unsigned v[8];
; #pragma unroll
;             for (int i = 0; i < 8; ++i) v[i] = th[(k8 + i) * 74 + nn];
;             u32x4 w; w.x = v[0] | (v[1] << 16); w.y = v[2] | (v[3] << 16); w.z = v[4] | (v[5] << 16); w.w = v[6] | (v[7] << 16);
;             *(u32x4*)(dst + (size_t)(n0 + nn) * 4096 + k0 + t * 256 + k8) = w;
.LBB0_1407:
	s_or_b64 exec, exec, s[0:1]
	s_barrier
	s_waitcnt vmcnt(12)
	v_cvt_pk_bf16_f32 v16, v16, v17
	ds_write_b32 v65, v16
	v_cvt_pk_bf16_f32 v16, v18, v19
	ds_write_b32 v65, v16 offset:4
	v_cvt_pk_bf16_f32 v8, v8, v9
	ds_write_b32 v65, v8 offset:8
	v_cvt_pk_bf16_f32 v8, v10, v11
	ds_write_b32 v65, v8 offset:12
	v_cvt_pk_bf16_f32 v8, v24, v25
	ds_write_b32 v65, v8 offset:9472
	v_cvt_pk_bf16_f32 v8, v26, v27
	ds_write_b32 v65, v8 offset:9476
	v_cvt_pk_bf16_f32 v0, v0, v1
	ds_write_b32 v65, v0 offset:9480
	v_cvt_pk_bf16_f32 v0, v2, v3
	ds_write_b32 v65, v0 offset:9484
	v_cvt_pk_bf16_f32 v0, v48, v49
	ds_write_b32 v65, v0 offset:18944
	v_cvt_pk_bf16_f32 v0, v50, v51
	ds_write_b32 v65, v0 offset:18948
	v_cvt_pk_bf16_f32 v0, v44, v45
	ds_write_b32 v65, v0 offset:18952
	v_cvt_pk_bf16_f32 v0, v46, v47
	ds_write_b32 v65, v0 offset:18956
	v_cvt_pk_bf16_f32 v0, v60, v61
	ds_write_b32 v65, v0 offset:28416
	v_cvt_pk_bf16_f32 v0, v62, v63
	ds_write_b32 v65, v0 offset:28420
	v_cvt_pk_bf16_f32 v0, v36, v37
	ds_write_b32 v65, v0 offset:28424
	v_cvt_pk_bf16_f32 v0, v38, v39
	v_add_u32_e32 v70, v70, v72
	ds_write_b32 v65, v0 offset:28428
	s_waitcnt lgkmcnt(0)
	s_barrier
	ds_read_u16 v0, v70
	ds_read_u16 v1, v70 offset:148
	ds_read_u16 v2, v70 offset:296
	ds_read_u16 v3, v70 offset:444
	ds_read_u16 v8, v70 offset:592
	ds_read_u16 v9, v70 offset:740
	ds_read_u16 v10, v70 offset:888
	ds_read_u16 v11, v70 offset:1036
	s_waitcnt lgkmcnt(6)
	v_lshl_or_b32 v0, v1, 16, v0
	s_waitcnt lgkmcnt(4)
	v_lshl_or_b32 v1, v3, 16, v2
	s_waitcnt lgkmcnt(2)
	v_lshl_or_b32 v2, v9, 16, v8
	s_waitcnt lgkmcnt(0)
	v_lshl_or_b32 v3, v11, 16, v10
	ds_read_u16 v8, v70 offset:9472
	ds_read_u16 v9, v70 offset:9620
	ds_read_u16 v10, v70 offset:9768
	ds_read_u16 v11, v70 offset:9916
	ds_read_u16 v16, v70 offset:10064
	ds_read_u16 v17, v70 offset:10212
	ds_read_u16 v18, v70 offset:10360
	ds_read_u16 v19, v70 offset:10508
	global_store_dwordx4 v[66:67], v[0:3], off offset:512
	s_waitcnt lgkmcnt(6)
	s_nop 0
	v_lshl_or_b32 v0, v9, 16, v8
	s_waitcnt lgkmcnt(4)
	v_lshl_or_b32 v1, v11, 16, v10
	s_waitcnt lgkmcnt(2)
	v_lshl_or_b32 v2, v17, 16, v16
	s_waitcnt lgkmcnt(0)
	v_lshl_or_b32 v3, v19, 16, v18
	ds_read_u16 v8, v70 offset:18944
	ds_read_u16 v9, v70 offset:19092
	ds_read_u16 v10, v70 offset:19240
	ds_read_u16 v11, v70 offset:19388
	ds_read_u16 v16, v70 offset:19536
	ds_read_u16 v17, v70 offset:19684
	ds_read_u16 v18, v70 offset:19832
	ds_read_u16 v19, v70 offset:19980
	global_store_dwordx4 v[66:67], v[0:3], off offset:640
	s_waitcnt lgkmcnt(6)
	s_nop 0
	v_lshl_or_b32 v0, v9, 16, v8
	s_waitcnt lgkmcnt(4)
	v_lshl_or_b32 v1, v11, 16, v10
	s_waitcnt lgkmcnt(2)
	v_lshl_or_b32 v2, v17, 16, v16
	s_waitcnt lgkmcnt(0)
	v_lshl_or_b32 v3, v19, 16, v18
	ds_read_u16 v8, v70 offset:28416
	ds_read_u16 v9, v70 offset:28564
	ds_read_u16 v10, v70 offset:28712
	ds_read_u16 v11, v70 offset:28860
	ds_read_u16 v16, v70 offset:29008
	ds_read_u16 v17, v70 offset:29156
	ds_read_u16 v18, v70 offset:29304
	ds_read_u16 v19, v70 offset:29452
	global_store_dwordx4 v[66:67], v[0:3], off offset:768
	s_waitcnt lgkmcnt(6)
	s_nop 0
	v_lshl_or_b32 v0, v9, 16, v8
	s_waitcnt lgkmcnt(4)
	v_lshl_or_b32 v1, v11, 16, v10
	s_waitcnt lgkmcnt(2)
	v_lshl_or_b32 v2, v17, 16, v16
	s_waitcnt lgkmcnt(0)
	v_lshl_or_b32 v3, v19, 16, v18
	global_store_dwordx4 v[66:67], v[0:3], off offset:896
	v_mov_b32_e32 v8, 0
	v_mov_b32_e32 v9, 0
	v_mov_b32_e32 v0, 0
	v_mov_b32_e32 v10, 0
	v_mov_b32_e32 v11, 0
	v_mov_b32_e32 v16, 0
	v_mov_b32_e32 v17, 0
	v_mov_b32_e32 v18, 0
	v_mov_b32_e32 v19, 0
	s_and_saveexec_b64 s[0:1], vcc
	s_cbranch_execz .LBB0_1409
	v_add_u32_e32 v1, 0x300, v64
	v_mad_i64_i32 v[2:3], s[2:3], v1, s76, v[68:69]
	global_load_dwordx4 v[8:11], v[2:3], off offset:16
	global_load_dwordx4 v[16:19], v[2:3], off

; #define LAS __attribute__((address_space(3)))
;     template <class T> __device__ __forceinline__ T* w(size_t off) const { return (T*)(pp->ws + off); }
; __device__ __forceinline__ unsigned pk2(float lo, float hi) { return pg8::cvt_pk_bf16(lo, hi); }
; #define CT_LOAD(R, kbase) do { _Pragma("unroll") for (int _it = 0; _it < 4; ++_it) { R[_it][0] = (f32x4){0.f, 0.f, 0.f, 0.f}; R[_it][1] = (f32x4){0.f, 0.f, 0.f, 0.f}; \
;         if (sc >= 0) { const float* _p = src + (size_t)((kbase) + kk + 64 * _it) * src_ld + sc; R[_it][0] = *(const f32x4*)_p; R[_it][1] = *(const f32x4*)(_p + 4); } } } while (0)
; template <bool MAP, int NT>
; __device__ __forceinline__ void convert_tiles(const Ctx& c, const float* src, int src_ld, bf16* dst, int n0, int k0) {
;     ...
;         if (t + 1 < NT) CT_LOAD(rb, k0 + (t + 1) * 256);
;         if (t) __syncthreads();
; #pragma unroll
;         for (int it = 0; it < 4; ++it) {
;             LAS unsigned* tp = tile + (kk + 64 * it) * 37 + (c8 >> 1);
;             tp[0] = pk2(ra[it][0][0], ra[it][0][1]); tp[1] = pk2(ra[it][0][2], ra[it][0][3]); tp[2] = pk2(ra[it][1][0], ra[it][1][1]); tp[3] = pk2(ra[it][1][2], ra[it][1][3]);
;         }
;         __syncthreads();
;         const LAS bf16* th = (const LAS bf16*)tile;
; #pragma unroll
;         for (int it = 0; it < 4; ++it) {
;             const int k8 = ks * 8 + 64 * it;
;             unsigned v[8];
; #pragma unroll
;             for (int i = 0; i < 8; ++i) v[i] = th[(k8 + i) * 74 + nn];
;             u32x4 w; w.x = v[0] | (v[1] << 16); w.y = v[2] | (v[3] << 16); w.z = v[4] | (v[5] << 16); w.w = v[6] | (v[7] << 16);
;             *(u32x4*)(dst + (size_t)(n0 + nn) * 4096 + k0 + t * 256 + k8) = w;
.LBB0_1415:
	s_or_b64 exec, exec, s[0:1]
	s_barrier
	s_waitcnt vmcnt(12)
	v_cvt_pk_bf16_f32 v20, v20, v21
	ds_write_b32 v65, v20
	v_cvt_pk_bf16_f32 v20, v22, v23
	ds_write_b32 v65, v20 offset:4
	v_cvt_pk_bf16_f32 v12, v12, v13
	ds_write_b32 v65, v12 offset:8
	v_cvt_pk_bf16_f32 v12, v14, v15
	ds_write_b32 v65, v12 offset:12
	v_cvt_pk_bf16_f32 v12, v32, v33
	ds_write_b32 v65, v12 offset:9472
	v_cvt_pk_bf16_f32 v12, v34, v35
	ds_write_b32 v65, v12 offset:9476
	v_cvt_pk_bf16_f32 v4, v4, v5
	ds_write_b32 v65, v4 offset:9480
	v_cvt_pk_bf16_f32 v4, v6, v7
	ds_write_b32 v65, v4 offset:9484
	v_cvt_pk_bf16_f32 v4, v52, v53
	ds_write_b32 v65, v4 offset:18944
	v_cvt_pk_bf16_f32 v4, v54, v55
	ds_write_b32 v65, v4 offset:18948
	v_cvt_pk_bf16_f32 v4, v40, v41
	ds_write_b32 v65, v4 offset:18952
	v_cvt_pk_bf16_f32 v4, v42, v43
	ds_write_b32 v65, v4 offset:18956
	v_cvt_pk_bf16_f32 v4, v56, v57
	ds_write_b32 v65, v4 offset:28416
	v_cvt_pk_bf16_f32 v4, v58, v59
	ds_write_b32 v65, v4 offset:28420
	v_cvt_pk_bf16_f32 v4, v28, v29
	ds_write_b32 v65, v4 offset:28424
	v_cvt_pk_bf16_f32 v4, v30, v31
	ds_write_b32 v65, v4 offset:28428
	s_waitcnt lgkmcnt(0)
	s_barrier
	ds_read_u16 v4, v70
	ds_read_u16 v5, v70 offset:148
	ds_read_u16 v6, v70 offset:296
	ds_read_u16 v7, v70 offset:444
	ds_read_u16 v12, v70 offset:592
	ds_read_u16 v13, v70 offset:740
	ds_read_u16 v14, v70 offset:888
	ds_read_u16 v15, v70 offset:1036
	s_waitcnt lgkmcnt(6)
	v_lshl_or_b32 v4, v5, 16, v4
	s_waitcnt lgkmcnt(4)
	v_lshl_or_b32 v5, v7, 16, v6
	s_waitcnt lgkmcnt(2)
	v_lshl_or_b32 v6, v13, 16, v12
	s_waitcnt lgkmcnt(0)
	v_lshl_or_b32 v7, v15, 16, v14
	ds_read_u16 v12, v70 offset:9472
	ds_read_u16 v13, v70 offset:9620
	ds_read_u16 v14, v70 offset:9768
	ds_read_u16 v15, v70 offset:9916
	ds_read_u16 v20, v70 offset:10064
	ds_read_u16 v21, v70 offset:10212
	ds_read_u16 v22, v70 offset:10360
	ds_read_u16 v23, v70 offset:10508
	global_store_dwordx4 v[66:67], v[4:7], off offset:1024
	s_waitcnt lgkmcnt(6)
	s_nop 0
	v_lshl_or_b32 v4, v13, 16, v12
	s_waitcnt lgkmcnt(4)
	v_lshl_or_b32 v5, v15, 16, v14
	s_waitcnt lgkmcnt(2)
	v_lshl_or_b32 v6, v21, 16, v20
	s_waitcnt lgkmcnt(0)
	v_lshl_or_b32 v7, v23, 16, v22
	ds_read_u16 v12, v70 offset:18944
	ds_read_u16 v13, v70 offset:19092
	ds_read_u16 v14, v70 offset:19240
	ds_read_u16 v15, v70 offset:19388
	ds_read_u16 v20, v70 offset:19536
	ds_read_u16 v21, v70 offset:19684
	ds_read_u16 v22, v70 offset:19832
	ds_read_u16 v23, v70 offset:19980
	global_store_dwordx4 v[66:67], v[4:7], off offset:1152
	s_waitcnt lgkmcnt(6)
	s_nop 0
	v_lshl_or_b32 v4, v13, 16, v12
	s_waitcnt lgkmcnt(4)
	v_lshl_or_b32 v5, v15, 16, v14
	s_waitcnt lgkmcnt(2)
	v_lshl_or_b32 v6, v21, 16, v20
	s_waitcnt lgkmcnt(0)
	v_lshl_or_b32 v7, v23, 16, v22
	ds_read_u16 v12, v70 offset:28416
	ds_read_u16 v13, v70 offset:28564
	ds_read_u16 v14, v70 offset:28712
	ds_read_u16 v15, v70 offset:28860
	ds_read_u16 v20, v70 offset:29008
	ds_read_u16 v21, v70 offset:29156
	ds_read_u16 v22, v70 offset:29304
	ds_read_u16 v23, v70 offset:29452
	global_store_dwordx4 v[66:67], v[4:7], off offset:1280
	s_waitcnt lgkmcnt(6)
	s_nop 0
	v_lshl_or_b32 v4, v13, 16, v12
	s_waitcnt lgkmcnt(4)
	v_lshl_or_b32 v5, v15, 16, v14
	s_waitcnt lgkmcnt(2)
	v_lshl_or_b32 v6, v21, 16, v20
	s_waitcnt lgkmcnt(0)
	v_lshl_or_b32 v7, v23, 16, v22
	global_store_dwordx4 v[66:67], v[4:7], off offset:1408
	s_barrier
	s_waitcnt vmcnt(4)
	v_cvt_pk_bf16_f32 v4, v16, v17
	ds_write_b32 v65, v4
	v_cvt_pk_bf16_f32 v4, v18, v19
	ds_write_b32 v65, v4 offset:4
	v_cvt_pk_bf16_f32 v4, v8, v9
	ds_write_b32 v65, v4 offset:8
	v_cvt_pk_bf16_f32 v4, v10, v11
	ds_write_b32 v65, v4 offset:12
	v_cvt_pk_bf16_f32 v4, v36, v37
	ds_write_b32 v65, v4 offset:9472
	v_cvt_pk_bf16_f32 v4, v38, v39
	ds_write_b32 v65, v4 offset:9476
	v_cvt_pk_bf16_f32 v0, v0, v1
	ds_write_b32 v65, v0 offset:9480
	v_cvt_pk_bf16_f32 v0, v2, v3
	ds_write_b32 v65, v0 offset:9484
	v_cvt_pk_bf16_f32 v0, v48, v49
	ds_write_b32 v65, v0 offset:18944
	v_cvt_pk_bf16_f32 v0, v50, v51
	ds_write_b32 v65, v0 offset:18948
	v_cvt_pk_bf16_f32 v0, v44, v45
	ds_write_b32 v65, v0 offset:18952
	v_cvt_pk_bf16_f32 v0, v46, v47
	ds_write_b32 v65, v0 offset:18956
	v_cvt_pk_bf16_f32 v0, v60, v61
	ds_write_b32 v65, v0 offset:28416
	v_cvt_pk_bf16_f32 v0, v62, v63
	ds_write_b32 v65, v0 offset:28420
	v_cvt_pk_bf16_f32 v0, v24, v25
	ds_write_b32 v65, v0 offset:28424
	v_cvt_pk_bf16_f32 v0, v26, v27
	ds_write_b32 v65, v0 offset:28428
	s_waitcnt lgkmcnt(0)
	s_barrier
	ds_read_u16 v0, v70
	ds_read_u16 v1, v70 offset:148
	ds_read_u16 v2, v70 offset:296
	ds_read_u16 v3, v70 offset:444
	ds_read_u16 v4, v70 offset:592
	ds_read_u16 v5, v70 offset:740
	ds_read_u16 v6, v70 offset:888
	ds_read_u16 v7, v70 offset:1036
	s_waitcnt lgkmcnt(6)
	v_lshl_or_b32 v0, v1, 16, v0
	s_waitcnt lgkmcnt(4)
	v_lshl_or_b32 v1, v3, 16, v2
	s_waitcnt lgkmcnt(2)
	v_lshl_or_b32 v2, v5, 16, v4
	s_waitcnt lgkmcnt(0)
	v_lshl_or_b32 v3, v7, 16, v6
	ds_read_u16 v4, v70 offset:9472
	ds_read_u16 v5, v70 offset:9620
	ds_read_u16 v6, v70 offset:9768
	ds_read_u16 v7, v70 offset:9916
	ds_read_u16 v8, v70 offset:10064
	ds_read_u16 v9, v70 offset:10212
	ds_read_u16 v10, v70 offset:10360
	ds_read_u16 v11, v70 offset:10508
	global_store_dwordx4 v[66:67], v[0:3], off offset:1536
	s_waitcnt lgkmcnt(6)
	s_nop 0
	v_lshl_or_b32 v0, v5, 16, v4
	s_waitcnt lgkmcnt(4)
	v_lshl_or_b32 v1, v7, 16, v6
	s_waitcnt lgkmcnt(2)
	v_lshl_or_b32 v2, v9, 16, v8
	s_waitcnt lgkmcnt(0)
	v_lshl_or_b32 v3, v11, 16, v10
	ds_read_u16 v4, v70 offset:18944
	ds_read_u16 v5, v70 offset:19092
	ds_read_u16 v6, v70 offset:19240
	ds_read_u16 v7, v70 offset:19388
	ds_read_u16 v8, v70 offset:19536
	ds_read_u16 v9, v70 offset:19684
	ds_read_u16 v10, v70 offset:19832
	ds_read_u16 v11, v70 offset:19980
	global_store_dwordx4 v[66:67], v[0:3], off offset:1664
	s_waitcnt lgkmcnt(6)
	s_nop 0
	v_lshl_or_b32 v0, v5, 16, v4
	s_waitcnt lgkmcnt(4)
	v_lshl_or_b32 v1, v7, 16, v6
	s_waitcnt lgkmcnt(2)
	v_lshl_or_b32 v2, v9, 16, v8
	s_waitcnt lgkmcnt(0)
	v_lshl_or_b32 v3, v11, 16, v10
	ds_read_u16 v4, v70 offset:28416
	ds_read_u16 v5, v70 offset:28564
	ds_read_u16 v6, v70 offset:28712
	ds_read_u16 v7, v70 offset:28860
	ds_read_u16 v8, v70 offset:29008
	ds_read_u16 v9, v70 offset:29156
	ds_read_u16 v10, v70 offset:29304
	ds_read_u16 v11, v70 offset:29452
	global_store_dwordx4 v[66:67], v[0:3], off offset:1792
	s_waitcnt lgkmcnt(6)
	s_nop 0
	v_lshl_or_b32 v0, v5, 16, v4
	s_waitcnt lgkmcnt(4)
	v_lshl_or_b32 v1, v7, 16, v6
	s_waitcnt lgkmcnt(2)
	v_lshl_or_b32 v2, v9, 16, v8
	s_waitcnt lgkmcnt(0)
	v_lshl_or_b32 v3, v11, 16, v10
	global_store_dwordx4 v[66:67], v[0:3], off offset:1920
